# v22: up-GEMM sample tile: 8-way partial-sum reduction issues its 16 LDS reads up front (same add order)
# speedup vs baseline: 1.0272x; 1.0022x over previous
; template <int NT, int ACT, int K>
; __device__ __forceinline__ void small_gemm_tile(LAS unsigned char* lds, const bf16* __restrict__ A, const bf16* __restrict__ Bt, bf16* __restrict__ O, int ldc, int lda, int ldb, const float* __restrict__ rs, int m0, int n0, int tid) {
;     constexpr int NC = 16 * NT, KW = K / 8, NCH = KW / 128;
;     const int wave = __builtin_amdgcn_readfirstlane(tid >> 6), lane = tid & 63, fr = lane & 15, fq = lane >> 4;
;     const bf16* ap = A + (size_t)(m0 + fr) * lda + wave * KW + fq * 8;
;     const bf16* bp = Bt + (size_t)(n0 + fr) * ldb + wave * KW + fq * 8;
;     f32x4 acc[4][NT];
; #pragma unroll
;     for (int m = 0; m < 4; ++m)
; #pragma unroll
;         for (int n = 0; n < NT; ++n) acc[m][n] = (f32x4){0.f, 0.f, 0.f, 0.f};
;     if constexpr (NCH == 1) {
;         bf16x8 fa[4][4], fb[4][NT];
; #pragma unroll
;         for (int s_ = 0; s_ < 4; ++s_) {
; #pragma unroll
;             for (int m = 0; m < 4; ++m) fa[s_][m] = *(const bf16x8*)(ap + (size_t)m * 16 * lda + s_ * 32);
; #pragma unroll
;             for (int n = 0; n < NT; ++n) fb[s_][n] = *(const bf16x8*)(bp + (size_t)n * 16 * ldb + s_ * 32); }
;         __builtin_amdgcn_sched_barrier(0);
; #pragma unroll
;         for (int s_ = 0; s_ < 4; ++s_)
; #pragma unroll
;             for (int m = 0; m < 4; ++m)
; #pragma unroll
;                 for (int n = 0; n < NT; ++n) acc[m][n] = __builtin_amdgcn_mfma_f32_16x16x32_bf16(fa[s_][m], fb[s_][n], acc[m][n], 0, 0, 0);
;         __builtin_amdgcn_sched_barrier(0);
;     } else {
;         constexpr int NC2 = KW / 64;
;         bf16x8 fa[3][2][4], fb[3][2][NT];
;     ...
;         SG_LD(0, 0); SG_LD(1, 1);
;         __builtin_amdgcn_sched_barrier(0);
; #pragma unroll
;         for (int c = 0; c < NC2; ++c) {
;             if (c + 2 < NC2) SG_LD((c + 2) % 3, c + 2);
;             __builtin_amdgcn_sched_barrier(0);
; #pragma unroll
;             for (int s_ = 0; s_ < 2; ++s_)
; #pragma unroll
;                 for (int m = 0; m < 4; ++m)
; #pragma unroll
;                     for (int n = 0; n < NT; ++n) acc[m][n] = __builtin_amdgcn_mfma_f32_16x16x32_bf16(fa[c % 3][s_][m], fb[c % 3][s_][n], acc[m][n], 0, 0, 0);
;             __builtin_amdgcn_sched_barrier(0);
;         }
;     ...
;     }
;     LAS float* P = (LAS float*)lds + wave * (64 * NC);
; #pragma unroll
;     for (int m = 0; m < 4; ++m)
; #pragma unroll
;         for (int n = 0; n < NT; ++n)
.LBB0_60:
	s_and_b32 s5, s6, 0x1c0
	v_readfirstlane_b32 s8, v186
	s_bitset1_b32 s5, 14
	s_ashr_i32 s10, s8, 6
	s_lshl_b32 s8, s10, 7
	s_ashr_i32 s9, s8, 31
	s_lshl_b64 s[8:9], s[8:9], 1
	s_lshl_b32 s4, s7, 3
	s_andn2_b32 s4, s4, 63
	s_lshl_b32 s100, s5, 12
	s_add_u32 s100, s100, s18
	s_addc_u32 s101, s19, 0
	s_add_u32 s100, s100, s8
	s_addc_u32 s101, s101, s9
	s_add_u32 s8, s8, s0
	s_addc_u32 s9, s9, s1
	s_lshl_b32 vcc_lo, s4, 11
	s_add_u32 s8, s8, vcc_lo
	s_addc_u32 s9, s9, 0
	s_lshl_b32 m0, s10, 14
	s_nop 0
	global_load_lds_dwordx4 v212, s[100:101]
	s_add_i32 m0, m0, 0x400
	s_nop 0
	global_load_lds_dwordx4 v213, s[100:101]
	s_add_i32 m0, m0, 0x400
	s_nop 0
	global_load_lds_dwordx4 v214, s[100:101]
	s_add_i32 m0, m0, 0x400
	s_nop 0
	global_load_lds_dwordx4 v215, s[100:101]
	s_add_i32 m0, m0, 0x400
	s_nop 0
	global_load_lds_dwordx4 v216, s[100:101]
	s_add_i32 m0, m0, 0x400
	s_nop 0
	global_load_lds_dwordx4 v217, s[100:101]
	s_add_i32 m0, m0, 0x400
	s_nop 0
	global_load_lds_dwordx4 v218, s[100:101]
	s_add_i32 m0, m0, 0x400
	s_nop 0
	global_load_lds_dwordx4 v219, s[100:101]
	s_add_i32 m0, m0, 0x400
	s_nop 0
	global_load_lds_dwordx4 v220, s[8:9]
	s_add_i32 m0, m0, 0x400
	s_nop 0
	global_load_lds_dwordx4 v221, s[8:9]
	s_add_i32 m0, m0, 0x400
	s_nop 0
	global_load_lds_dwordx4 v222, s[8:9]
	s_add_i32 m0, m0, 0x400
	s_nop 0
	global_load_lds_dwordx4 v223, s[8:9]
	s_add_i32 m0, m0, 0x400
	s_nop 0
	global_load_lds_dwordx4 v224, s[8:9]
	s_add_i32 m0, m0, 0x400
	s_nop 0
	global_load_lds_dwordx4 v225, s[8:9]
	s_add_i32 m0, m0, 0x400
	s_nop 0
	global_load_lds_dwordx4 v226, s[8:9]
	s_add_i32 m0, m0, 0x400
	s_nop 0
	global_load_lds_dwordx4 v227, s[8:9]
	global_load_dwordx4 v[80:83], v212, s[100:101] offset:128
	global_load_dwordx4 v[84:87], v213, s[100:101] offset:128
	global_load_dwordx4 v[88:91], v214, s[100:101] offset:128
	global_load_dwordx4 v[92:95], v215, s[100:101] offset:128
	global_load_dwordx4 v[96:99], v216, s[100:101] offset:128
	global_load_dwordx4 v[100:103], v217, s[100:101] offset:128
	global_load_dwordx4 v[104:107], v218, s[100:101] offset:128
	global_load_dwordx4 v[108:111], v219, s[100:101] offset:128
	global_load_dwordx4 v[112:115], v220, s[8:9] offset:128
	global_load_dwordx4 v[116:119], v221, s[8:9] offset:128
	global_load_dwordx4 v[120:123], v222, s[8:9] offset:128
	global_load_dwordx4 v[124:127], v223, s[8:9] offset:128
	global_load_dwordx4 v[136:139], v224, s[8:9] offset:128
	global_load_dwordx4 v[140:143], v225, s[8:9] offset:128
	global_load_dwordx4 v[144:147], v226, s[8:9] offset:128
	global_load_dwordx4 v[148:151], v227, s[8:9] offset:128
	s_waitcnt vmcnt(16)
	ds_read_b128 v[16:19], v228 offset:0
	ds_read_b128 v[20:23], v229 offset:0
	ds_read_b128 v[24:27], v228 offset:2048
	ds_read_b128 v[28:31], v229 offset:2048
	ds_read_b128 v[32:35], v228 offset:4096
	ds_read_b128 v[36:39], v229 offset:4096
	ds_read_b128 v[40:43], v228 offset:6144
	ds_read_b128 v[44:47], v229 offset:6144
	ds_read_b128 v[48:51], v228 offset:8192
	ds_read_b128 v[52:55], v229 offset:8192
	ds_read_b128 v[56:59], v228 offset:10240
	ds_read_b128 v[60:63], v229 offset:10240
	ds_read_b128 v[64:67], v228 offset:12288
	ds_read_b128 v[68:71], v229 offset:12288
	ds_read_b128 v[72:75], v228 offset:14336
	ds_read_b128 v[76:79], v229 offset:14336
	s_waitcnt lgkmcnt(0)
	s_waitcnt vmcnt(0)
	ds_write_b128 v234, v[80:83]
	ds_write_b128 v234, v[84:87] offset:1024
	ds_write_b128 v234, v[88:91] offset:2048
	ds_write_b128 v234, v[92:95] offset:3072
	ds_write_b128 v234, v[96:99] offset:4096
	ds_write_b128 v234, v[100:103] offset:5120
	ds_write_b128 v234, v[104:107] offset:6144
	ds_write_b128 v234, v[108:111] offset:7168
	ds_write_b128 v234, v[112:115] offset:8192
	ds_write_b128 v234, v[116:119] offset:9216
	ds_write_b128 v234, v[120:123] offset:10240
	ds_write_b128 v234, v[124:127] offset:11264
	ds_write_b128 v234, v[136:139] offset:12288
	ds_write_b128 v234, v[140:143] offset:13312
	ds_write_b128 v234, v[144:147] offset:14336
	ds_write_b128 v234, v[148:151] offset:15360
	v_mfma_f32_16x16x32_bf16 v[154:157], v[16:19], v[48:51], 0
	v_mfma_f32_16x16x32_bf16 v[158:161], v[16:19], v[56:59], 0
	v_mfma_f32_16x16x32_bf16 v[162:165], v[16:19], v[64:67], 0
	v_mfma_f32_16x16x32_bf16 v[16:19], v[16:19], v[72:75], 0
	v_mfma_f32_16x16x32_bf16 v[188:191], v[24:27], v[48:51], 0
	v_mfma_f32_16x16x32_bf16 v[192:195], v[24:27], v[56:59], 0
	v_mfma_f32_16x16x32_bf16 v[196:199], v[24:27], v[64:67], 0
	v_mfma_f32_16x16x32_bf16 v[24:27], v[24:27], v[72:75], 0
	v_mfma_f32_16x16x32_bf16 v[200:203], v[32:35], v[48:51], 0
	v_mfma_f32_16x16x32_bf16 v[204:207], v[32:35], v[56:59], 0
	v_mfma_f32_16x16x32_bf16 v[208:211], v[32:35], v[64:67], 0
	v_mfma_f32_16x16x32_bf16 v[32:35], v[32:35], v[72:75], 0
	v_mfma_f32_16x16x32_bf16 v[48:51], v[40:43], v[48:51], 0
	v_mfma_f32_16x16x32_bf16 v[56:59], v[40:43], v[56:59], 0
	v_mfma_f32_16x16x32_bf16 v[64:67], v[40:43], v[64:67], 0
	v_mfma_f32_16x16x32_bf16 v[40:43], v[40:43], v[72:75], 0
	v_mfma_f32_16x16x32_bf16 v[72:75], v[20:23], v[52:55], v[154:157]
	v_mfma_f32_16x16x32_bf16 v[154:157], v[20:23], v[60:63], v[158:161]
	v_mfma_f32_16x16x32_bf16 v[158:161], v[20:23], v[68:71], v[162:165]
	v_mfma_f32_16x16x32_bf16 v[16:19], v[20:23], v[76:79], v[16:19]
	v_mfma_f32_16x16x32_bf16 v[20:23], v[28:31], v[52:55], v[188:191]
	v_mfma_f32_16x16x32_bf16 v[162:165], v[28:31], v[60:63], v[192:195]
	v_mfma_f32_16x16x32_bf16 v[188:191], v[28:31], v[68:71], v[196:199]
	v_mfma_f32_16x16x32_bf16 v[24:27], v[28:31], v[76:79], v[24:27]
	v_mfma_f32_16x16x32_bf16 v[28:31], v[36:39], v[52:55], v[200:203]
	v_mfma_f32_16x16x32_bf16 v[192:195], v[36:39], v[60:63], v[204:207]
	v_mfma_f32_16x16x32_bf16 v[196:199], v[36:39], v[68:71], v[208:211]
	v_mfma_f32_16x16x32_bf16 v[32:35], v[36:39], v[76:79], v[32:35]
	v_mfma_f32_16x16x32_bf16 v[36:39], v[44:47], v[52:55], v[48:51]
	v_mfma_f32_16x16x32_bf16 v[48:51], v[44:47], v[60:63], v[56:59]
	v_mfma_f32_16x16x32_bf16 v[52:55], v[44:47], v[68:71], v[64:67]
	v_mfma_f32_16x16x32_bf16 v[40:43], v[44:47], v[76:79], v[40:43]
	s_waitcnt lgkmcnt(0)
; #define LAS __attribute__((address_space(3)))
; #define SG_LD(buf, c) do { _Pragma("unroll") for (int s_ = 0; s_ < 2; ++s_) { \
;             _Pragma("unroll") for (int m = 0; m < 4; ++m) fa[buf][s_][m] = *(const bf16x8*)(ap + (size_t)m * 16 * lda + (c) * 64 + s_ * 32); \
;             _Pragma("unroll") for (int n = 0; n < NT; ++n) fb[buf][s_][n] = *(const bf16x8*)(bp + (size_t)n * 16 * ldb + (c) * 64 + s_ * 32); } } while (0)
; template <int NT, int ACT, int K>
; __device__ __forceinline__ void small_gemm_tile(LAS unsigned char* lds, const bf16* __restrict__ A, const bf16* __restrict__ Bt, bf16* __restrict__ O, int ldc, int lda, int ldb, const float* __restrict__ rs, int m0, int n0, int tid) {
;     ...
;         __builtin_amdgcn_sched_barrier(0);
; #pragma unroll
;         for (int s_ = 0; s_ < 4; ++s_)
; #pragma unroll
;             for (int m = 0; m < 4; ++m)
; #pragma unroll
;                 for (int n = 0; n < NT; ++n) acc[m][n] = __builtin_amdgcn_mfma_f32_16x16x32_bf16(fa[s_][m], fb[s_][n], acc[m][n], 0, 0, 0);
;         __builtin_amdgcn_sched_barrier(0);
;     } else {
;         constexpr int NC2 = KW / 64;
;         bf16x8 fa[3][2][4], fb[3][2][NT];
;     ...
;         SG_LD(0, 0); SG_LD(1, 1);
;         __builtin_amdgcn_sched_barrier(0);
; #pragma unroll
;         for (int c = 0; c < NC2; ++c) {
;             if (c + 2 < NC2) SG_LD((c + 2) % 3, c + 2);
;             __builtin_amdgcn_sched_barrier(0);
; #pragma unroll
;             for (int s_ = 0; s_ < 2; ++s_)
; #pragma unroll
;                 for (int m = 0; m < 4; ++m)
; #pragma unroll
;                     for (int n = 0; n < NT; ++n) acc[m][n] = __builtin_amdgcn_mfma_f32_16x16x32_bf16(fa[c % 3][s_][m], fb[c % 3][s_][n], acc[m][n], 0, 0, 0);
;             __builtin_amdgcn_sched_barrier(0);
;         }
;     ...
;     }
;     LAS float* P = (LAS float*)lds + wave * (64 * NC);
; #pragma unroll
;     for (int m = 0; m < 4; ++m)
; #pragma unroll
;         for (int n = 0; n < NT; ++n)
; #pragma unroll
;             for (int i = 0; i < 4; ++i) P[(m * 16 + fq * 4 + i) * NC + n * 16 + fr] = acc[m][n][i];
;     __syncthreads();
	ds_read_b128 v[80:83], v228 offset:0
	ds_read_b128 v[84:87], v229 offset:0
	ds_read_b128 v[88:91], v228 offset:2048
	ds_read_b128 v[92:95], v229 offset:2048
	ds_read_b128 v[96:99], v228 offset:4096
	ds_read_b128 v[100:103], v229 offset:4096
	ds_read_b128 v[104:107], v228 offset:6144
	ds_read_b128 v[108:111], v229 offset:6144
	ds_read_b128 v[112:115], v228 offset:8192
	ds_read_b128 v[116:119], v229 offset:8192
	ds_read_b128 v[120:123], v228 offset:10240
	ds_read_b128 v[124:127], v229 offset:10240
	ds_read_b128 v[136:139], v228 offset:12288
	ds_read_b128 v[140:143], v229 offset:12288
	ds_read_b128 v[144:147], v228 offset:14336
	ds_read_b128 v[148:151], v229 offset:14336
	s_waitcnt lgkmcnt(0)
	v_mfma_f32_16x16x32_bf16 v[44:47], v[80:83], v[112:115], v[72:75]
	v_mfma_f32_16x16x32_bf16 v[56:59], v[80:83], v[120:123], v[154:157]
	v_mfma_f32_16x16x32_bf16 v[60:63], v[80:83], v[136:139], v[158:161]
	v_mfma_f32_16x16x32_bf16 v[16:19], v[80:83], v[144:147], v[16:19]
	v_mfma_f32_16x16x32_bf16 v[20:23], v[88:91], v[112:115], v[20:23]
	v_mfma_f32_16x16x32_bf16 v[64:67], v[88:91], v[120:123], v[162:165]
	v_mfma_f32_16x16x32_bf16 v[68:71], v[88:91], v[136:139], v[188:191]
	v_mfma_f32_16x16x32_bf16 v[24:27], v[88:91], v[144:147], v[24:27]
	v_mfma_f32_16x16x32_bf16 v[28:31], v[96:99], v[112:115], v[28:31]
	v_mfma_f32_16x16x32_bf16 v[72:75], v[96:99], v[120:123], v[192:195]
	v_mfma_f32_16x16x32_bf16 v[76:79], v[96:99], v[136:139], v[196:199]
	v_mfma_f32_16x16x32_bf16 v[32:35], v[96:99], v[144:147], v[32:35]
	v_mfma_f32_16x16x32_bf16 v[36:39], v[104:107], v[112:115], v[36:39]
	v_mfma_f32_16x16x32_bf16 v[48:51], v[104:107], v[120:123], v[48:51]
	v_mfma_f32_16x16x32_bf16 v[52:55], v[104:107], v[136:139], v[52:55]
	v_mfma_f32_16x16x32_bf16 v[40:43], v[104:107], v[144:147], v[40:43]
	v_mfma_f32_16x16x32_bf16 v[44:47], v[84:87], v[116:119], v[44:47]
	v_mfma_f32_16x16x32_bf16 v[56:59], v[84:87], v[124:127], v[56:59]
	v_mfma_f32_16x16x32_bf16 v[60:63], v[84:87], v[140:143], v[60:63]
	v_mfma_f32_16x16x32_bf16 v[16:19], v[84:87], v[148:151], v[16:19]
	v_mfma_f32_16x16x32_bf16 v[20:23], v[92:95], v[116:119], v[20:23]
	v_mfma_f32_16x16x32_bf16 v[64:67], v[92:95], v[124:127], v[64:67]
	v_mfma_f32_16x16x32_bf16 v[68:71], v[92:95], v[140:143], v[68:71]
	v_mfma_f32_16x16x32_bf16 v[24:27], v[92:95], v[148:151], v[24:27]
	v_mfma_f32_16x16x32_bf16 v[28:31], v[100:103], v[116:119], v[28:31]
	v_mfma_f32_16x16x32_bf16 v[72:75], v[100:103], v[124:127], v[72:75]
	v_mfma_f32_16x16x32_bf16 v[76:79], v[100:103], v[140:143], v[76:79]
	v_mfma_f32_16x16x32_bf16 v[32:35], v[100:103], v[148:151], v[32:35]
	v_mfma_f32_16x16x32_bf16 v[36:39], v[108:111], v[116:119], v[36:39]
	v_mfma_f32_16x16x32_bf16 v[48:51], v[108:111], v[124:127], v[48:51]
	v_mfma_f32_16x16x32_bf16 v[52:55], v[108:111], v[140:143], v[52:55]
	v_mfma_f32_16x16x32_bf16 v[40:43], v[108:111], v[148:151], v[40:43]
	v_lshl_add_u32 v3, s10, 14, v14
	v_add_u32_e32 v15, 0x1000, v3
	ds_write2_b32 v3, v44, v56 offset1:16
	ds_write2_b32 v3, v45, v57 offset0:64 offset1:80
	ds_write2_b32 v3, v46, v58 offset0:128 offset1:144
	ds_write2_b32 v3, v47, v59 offset0:192 offset1:208
	ds_write2_b32 v3, v60, v16 offset0:32 offset1:48
	ds_write2_b32 v3, v61, v17 offset0:96 offset1:112
	ds_write2_b32 v3, v62, v18 offset0:160 offset1:176
	ds_write2_b32 v3, v63, v19 offset0:224 offset1:240
	ds_write2_b32 v15, v20, v64 offset1:16
	ds_write2_b32 v15, v21, v65 offset0:64 offset1:80
	ds_write2_b32 v15, v22, v66 offset0:128 offset1:144
	ds_write2_b32 v15, v23, v67 offset0:192 offset1:208
	ds_write2_b32 v15, v68, v24 offset0:32 offset1:48
	ds_write2_b32 v15, v69, v25 offset0:96 offset1:112
	ds_write2_b32 v15, v70, v26 offset0:160 offset1:176
	ds_write2_b32 v15, v71, v27 offset0:224 offset1:240
	v_add_u32_e32 v24, s5, v13
	v_ashrrev_i32_e32 v25, 31, v24
	v_add_u32_e32 v15, 0x2000, v3
	v_add_u32_e32 v3, 0x3000, v3
	v_lshl_add_u64 v[20:21], v[24:25], 2, s[82:83]
	ds_write2_b32 v15, v28, v72 offset1:16
	ds_write2_b32 v15, v29, v73 offset0:64 offset1:80
	ds_write2_b32 v15, v30, v74 offset0:128 offset1:144
	ds_write2_b32 v15, v31, v75 offset0:192 offset1:208
	ds_write2_b32 v15, v76, v32 offset0:32 offset1:48
	ds_write2_b32 v15, v77, v33 offset0:96 offset1:112
	ds_write2_b32 v15, v78, v34 offset0:160 offset1:176
	ds_write2_b32 v15, v79, v35 offset0:224 offset1:240
	ds_write2_b32 v3, v36, v48 offset1:16
	ds_write2_b32 v3, v37, v49 offset0:64 offset1:80
	ds_write2_b32 v3, v38, v50 offset0:128 offset1:144
	ds_write2_b32 v3, v39, v51 offset0:192 offset1:208
	ds_write2_b32 v3, v52, v40 offset0:32 offset1:48
	ds_write2_b32 v3, v53, v41 offset0:96 offset1:112
	ds_write2_b32 v3, v54, v42 offset0:160 offset1:176
	ds_write2_b32 v3, v55, v43 offset0:224 offset1:240
	s_waitcnt lgkmcnt(0)
	s_barrier
; #define LAS __attribute__((address_space(3)))
; __device__ __forceinline__ unsigned pk2(float lo, float hi) { return f2bf(lo) | (f2bf(hi) << 16); }
; template <int NT, int ACT, int K>
; __device__ __forceinline__ void small_gemm_tile(LAS unsigned char* lds, const bf16* __restrict__ A, const bf16* __restrict__ Bt, bf16* __restrict__ O, int ldc, int lda, int ldb, const float* __restrict__ rs, int m0, int n0, int tid) {
;     ...
;     constexpr int EPT = 64 * NC / 512;
;     const int e0 = tid * EPT, row = e0 / NC, col = e0 % NC;
;     float r[EPT];
; #pragma unroll
;     for (int j = 0; j < EPT; ++j) r[j] = 0.f;
; #pragma unroll
;     for (int w = 0; w < 8; ++w) { const LAS f32x4* q = (const LAS f32x4*)((LAS float*)lds + w * (64 * NC) + e0);
; #pragma unroll
;         for (int j = 0; j < EPT / 4; ++j) { const f32x4 v = q[j]; r[4 * j] += v[0]; r[4 * j + 1] += v[1]; r[4 * j + 2] += v[2]; r[4 * j + 3] += v[3]; } }
;     if (rs) { const float sc = rs[m0 + row];
; #pragma unroll
;         for (int j = 0; j < EPT; ++j) r[j] *= sc; }
;     if (ACT == 1) {
; #pragma unroll
;         for (int j = 0; j < EPT; ++j) { const float t = fmaxf(r[j], 0.f); r[j] = t * t; } }
;     bf16* op = O + (size_t)(m0 + row) * ldc + n0 + col;
;     if (EPT == 8) { v4u w; w.x = pk2(r[0], r[1]); w.y = pk2(r[2], r[3]); w.z = pk2(r[4 % EPT], r[5 % EPT]); w.w = pk2(r[6 % EPT], r[7 % EPT]); *(v4u*)op = w; }
;     else { v2u w; w.x = pk2(r[0], r[1]); w.y = pk2(r[2], r[3]); *(v2u*)op = w; }
;     __syncthreads();
	global_load_dword v3, v[20:21], off
	ds_read_b128 v[80:83], v4
	ds_read_b128 v[84:87], v4 offset:16
	ds_read_b128 v[88:91], v4 offset:16384
	ds_read_b128 v[92:95], v4 offset:16400
	ds_read_b128 v[96:99], v4 offset:32768
	ds_read_b128 v[100:103], v4 offset:32784
	ds_read_b128 v[104:107], v4 offset:49152
	ds_read_b128 v[108:111], v4 offset:49168
	ds_read_b128 v[112:115], v5
	ds_read_b128 v[116:119], v6
	ds_read_b128 v[120:123], v7
	ds_read_b128 v[124:127], v8
	ds_read_b128 v[136:139], v9
	ds_read_b128 v[140:143], v10
	ds_read_b128 v[144:147], v11
	ds_read_b128 v[148:151], v12
	s_movk_i32 s5, 0x2080
	s_add_i32 s7, s7, s3
	s_add_i32 s6, s6, s2
	s_waitcnt lgkmcnt(0)
	v_add_f32_e32 v15, 0, v80
	v_add_f32_e32 v25, 0, v81
	v_add_f32_e32 v26, 0, v82
	v_add_f32_e32 v27, 0, v83
	v_add_f32_e32 v28, 0, v84
	v_add_f32_e32 v29, 0, v85
	v_add_f32_e32 v30, 0, v86
	v_add_f32_e32 v31, 0, v87
	v_add_f32_e32 v15, v15, v88
	v_add_f32_e32 v25, v25, v89
	v_add_f32_e32 v26, v26, v90
	v_add_f32_e32 v27, v27, v91
	v_add_f32_e32 v28, v28, v92
	v_add_f32_e32 v29, v29, v93
	v_add_f32_e32 v30, v30, v94
	v_add_f32_e32 v31, v31, v95
	v_add_f32_e32 v15, v15, v96
	v_add_f32_e32 v25, v25, v97
	v_add_f32_e32 v26, v26, v98
	v_add_f32_e32 v27, v27, v99
	v_add_f32_e32 v28, v28, v100
	v_add_f32_e32 v29, v29, v101
	v_add_f32_e32 v30, v30, v102
	v_add_f32_e32 v31, v31, v103
	v_add_f32_e32 v15, v15, v104
	v_add_f32_e32 v25, v25, v105
	v_add_f32_e32 v26, v26, v106
	v_add_f32_e32 v27, v27, v107
	v_add_f32_e32 v28, v28, v108
	v_add_f32_e32 v29, v29, v109
	v_add_f32_e32 v30, v30, v110
	v_add_f32_e32 v31, v31, v111
	v_add_f32_e32 v15, v15, v112
	v_add_f32_e32 v25, v25, v113
	v_add_f32_e32 v26, v26, v114
	v_add_f32_e32 v27, v27, v115
	v_add_f32_e32 v28, v28, v116
	v_add_f32_e32 v29, v29, v117
	v_add_f32_e32 v30, v30, v118
	v_add_f32_e32 v31, v31, v119
	v_add_f32_e32 v15, v15, v120
	v_add_f32_e32 v25, v25, v121
	v_add_f32_e32 v26, v26, v122
	v_add_f32_e32 v27, v27, v123
	v_add_f32_e32 v28, v28, v124
	v_add_f32_e32 v29, v29, v125
	v_add_f32_e32 v30, v30, v126
	v_add_f32_e32 v31, v31, v127
	v_add_f32_e32 v15, v15, v136
	v_add_f32_e32 v25, v25, v137
	v_add_f32_e32 v26, v26, v138
	v_add_f32_e32 v27, v27, v139
	v_add_f32_e32 v28, v28, v140
	v_add_f32_e32 v29, v29, v141
	v_add_f32_e32 v30, v30, v142
	v_add_f32_e32 v31, v31, v143
	v_add_f32_e32 v15, v15, v144
	v_add_f32_e32 v16, v25, v145
	v_add_f32_e32 v17, v26, v146
	v_add_f32_e32 v18, v27, v147
	v_add_f32_e32 v19, v28, v148
	v_add_f32_e32 v20, v29, v149
	v_add_f32_e32 v21, v30, v150
	v_add_f32_e32 v22, v31, v151
	s_waitcnt vmcnt(0)
	v_mul_f32_e32 v15, v3, v15
	v_mul_f32_e32 v23, v3, v16
	v_mul_f32_e32 v17, v3, v17
	v_mul_f32_e32 v25, v3, v18
	v_mul_f32_e32 v26, v3, v19
	v_mul_f32_e32 v27, v3, v20
	v_mul_f32_e32 v21, v3, v21
	v_mul_f32_e32 v3, v3, v22
	v_max_f32_e32 v18, 0, v23
	v_max_f32_e32 v19, 0, v25
	v_max_f32_e32 v22, 0, v27
	v_max_f32_e32 v23, 0, v3
	v_max_f32_e32 v16, 0, v15
	v_max_f32_e32 v17, 0, v17
	v_max_f32_e32 v20, 0, v26
	v_max_f32_e32 v21, 0, v21
	v_mov_b64_e32 v[26:27], s[64:65]
	v_pk_mul_f32 v[18:19], v[18:19], v[18:19]
	v_pk_mul_f32 v[22:23], v[22:23], v[22:23]
	v_mad_i64_i32 v[24:25], s[8:9], v24, s5, v[26:27]
	v_pk_mul_f32 v[16:17], v[16:17], v[16:17]
	v_pk_mul_f32 v[20:21], v[20:21], v[20:21]
	v_bfe_u32 v3, v23, 16, 1
	v_bfe_u32 v15, v22, 16, 1
	v_bfe_u32 v26, v19, 16, 1
	v_bfe_u32 v27, v18, 16, 1
	v_add3_u32 v27, v18, v27, s90
	v_add3_u32 v26, v19, v26, s90
	v_add3_u32 v15, v22, v15, s90
	v_add3_u32 v3, v23, v3, s90
	v_bfe_u32 v18, v16, 16, 1
	v_bfe_u32 v19, v17, 16, 1
	v_bfe_u32 v22, v20, 16, 1
	v_bfe_u32 v23, v21, 16, 1
	s_ashr_i32 s5, s4, 31
	v_add3_u32 v21, v21, v23, s90
	v_add3_u32 v20, v20, v22, s90
	v_add3_u32 v17, v17, v19, s90
	v_add3_u32 v16, v16, v18, s90
	v_lshl_add_u64 v[24:25], s[4:5], 1, v[24:25]
	v_lshrrev_b32_e32 v16, 16, v16
	v_lshrrev_b32_e32 v17, 16, v17
	v_lshrrev_b32_e32 v18, 16, v20
	v_lshrrev_b32_e32 v19, 16, v21
	v_lshl_add_u64 v[24:25], v[0:1], 1, v[24:25]
	v_and_or_b32 v19, v3, s91, v19
	v_and_or_b32 v18, v15, s91, v18
	v_and_or_b32 v17, v26, s91, v17
	v_and_or_b32 v16, v27, s91, v16
	s_cmpk_gt_i32 s7, 0x1ff
	global_store_dwordx4 v[24:25], v[16:19], off
	s_barrier
	s_cbranch_scc0 .LBB0_60
